# deferred weight transposition, 4-way stagger: layer l+1 weights converted inside PD of layer l by a quarter of the workgroups at each of four points (before PD work, between the latent units, after th
# baseline (speedup 1.0000x reference)
.LBB0_638:
	v_readlane_b32 s4, v255, 2
	v_readlane_b32 s6, v255, 4
	v_readlane_b32 s5, v255, 3
	s_cmp_gt_i32 s6, s56
	s_mul_i32 s6, s92, 6
	v_readlane_b32 s7, v255, 5
	s_cselect_b64 s[2:3], -1, 0
	s_xor_b64 s[4:5], s[18:19], -1
	s_add_i32 s37, s6, 5
	s_cmp_lt_i32 s37, s7
	s_cselect_b64 s[96:97], -1, 0
	s_or_b64 s[2:3], s[2:3], s[4:5]
	s_and_b64 vcc, exec, s[2:3]
	s_cbranch_vccnz .LBB0_823
	s_cmp_ge_u32 s92, 3
	s_cbranch_scc1 .Ltq1_exit
	s_cmpk_lg_i32 s13, 0x100
	s_cbranch_scc1 .Ltq1_go
	s_bfe_u32 s2, s12, 0x20003
	s_cmp_lg_u32 s2, 0
	s_cbranch_scc1 .Ltq1_exit
.Ltq1_go:
	v_and_b32_e32 v46, 63, v220
	v_readfirstlane_b32 s2, v220
	s_ashr_i32 s43, s2, 6
	s_lshl_b32 s2, s12, 3
	s_add_i32 s29, s43, s2
	s_add_u32 s48, s92, 1
	s_mul_i32 s48, s48, 0x3600
	s_add_u32 s29, s29, s48
	s_add_u32 s44, s48, 0x35ff
	s_cmp_gt_u32 s29, s44
	s_cbranch_scc1 .Ltq1_exit
	s_lshl_b32 s30, s13, 3
	s_load_dwordx2 s[2:3], s[0:1], 0x68
	s_load_dwordx2 s[4:5], s[0:1], 0xd0
	s_load_dwordx2 s[6:7], s[0:1], 0xc0
	s_load_dwordx2 s[38:39], s[0:1], 0xe8
	v_lshrrev_b32_e32 v0, 3, v46
	v_and_b32_e32 v1, 7, v46
	v_lshlrev_b32_e32 v2, 4, v1
	v_lshlrev_b32_e32 v3, 3, v0
	v_lshlrev_b32_e32 v4, 2, v1
	v_lshlrev_b32_e32 v5, 4, v0
	s_waitcnt lgkmcnt(0)
	s_mov_b32 s11, s29
	s_cmp_ge_u32 s11, 0x6c00
	s_cselect_b32 s80, 0x6c00, 0
	s_cselect_b32 s10, 2, 0
	s_sub_u32 s11, s11, s80
	s_cmp_ge_u32 s11, 0x3600
	s_cselect_b32 s80, 0x3600, 0
	s_cselect_b32 s81, 1, 0
	s_sub_u32 s11, s11, s80
	s_add_u32 s10, s10, s81
	s_cmp_lt_u32 s11, 0x2400
	s_cbranch_scc1 .Ltq1_in1
	s_cmp_lt_u32 s11, 0x3400
	s_cbranch_scc1 .Ltq1_out1
	s_sub_u32 s11, s11, 0x3400
	s_and_b32 s80, s11, 15
	s_lshr_b32 s81, s11, 4
	s_movk_i32 s78, 0x2000
	s_movk_i32 s79, 0x800
	s_mov_b32 s34, 0x10000
	s_lshl_b32 s31, s10, 23
	s_lshl_b32 s11, s80, 19
	s_add_u32 s31, s31, s11
	s_lshl_b32 s11, s81, 8
	s_add_u32 s31, s31, s11
	s_add_u32 s31, s6, s31
	s_addc_u32 s11, s7, 0
	s_bfe_u32 s78, s81, 0x30001
	s_lshl_b32 s78, s78, 8
	s_lshr_b32 s79, s81, 4
	s_lshl_b32 s79, s79, 7
	s_add_u32 s78, s78, s79
	s_and_b32 s79, s81, 1
	s_lshl_b32 s79, s79, 6
	s_add_u32 s78, s78, s79
	s_lshl_b32 s78, s78, 11
	s_lshl_b32 s79, s80, 7
	s_add_u32 s78, s78, s79
	s_lshl_b32 s79, s10, 22
	s_add_u32 s78, s78, s79
	s_add_u32 s81, s78, 0xae00000
	s_mov_b32 s80, s31
	s_mov_b32 s31, s81
	s_mov_b32 s81, s11
	s_movk_i32 s78, 0x2000
	s_movk_i32 s79, 0x800
	s_branch .Ltq1_dec1

.LBB0_705:
	v_readlane_b32 s2, v255, 34
	v_readlane_b32 s3, v255, 35
	s_andn2_b64 vcc, exec, s[2:3]
	s_cbranch_vccnz .LBB0_727
	s_lshl_b32 s8, s92, 18
	s_mov_b32 s9, s12
	s_branch .LBB0_708
.Ltramp271:
	s_branch .LBB0_271
.LBB0_707:
	s_or_b64 exec, exec, s[4:5]
	s_lshl_b32 s2, s10, 13
	s_add_u32 s3, s34, s2
	s_addc_u32 s2, s35, 0
	s_add_u32 s4, s11, s6
	s_addc_u32 s5, s15, s7
	v_lshrrev_b32_e32 v112, 4, v196
	v_lshl_add_u64 v[64:65], s[4:5], 0, v[176:177]
	v_or_b32_e32 v110, v112, v229
	v_lshl_add_u64 v[64:65], v[64:65], 0, s[66:67]
	s_waitcnt lgkmcnt(0)
	v_mad_i64_i32 v[66:67], s[4:5], v110, s45, v[64:65]
	v_or_b32_e32 v108, 4, v110
	v_or_b32_e32 v106, 8, v110
	v_mad_i64_i32 v[68:69], s[4:5], v108, s45, v[64:65]
	global_load_dwordx4 v[92:95], v[66:67], off
	global_load_dwordx4 v[88:91], v[68:69], off
	v_mad_i64_i32 v[66:67], s[4:5], v106, s45, v[64:65]
	v_or_b32_e32 v104, 12, v110
	v_or_b32_e32 v102, 16, v110
	v_mad_i64_i32 v[68:69], s[4:5], v104, s45, v[64:65]
	global_load_dwordx4 v[84:87], v[66:67], off
	global_load_dwordx4 v[80:83], v[68:69], off
	v_mad_i64_i32 v[66:67], s[4:5], v102, s45, v[64:65]
	v_or_b32_e32 v100, 20, v110
	v_lshl_add_u32 v99, v226, 4, v191
	v_mad_i64_i32 v[68:69], s[4:5], v100, s45, v[64:65]
	global_load_dwordx4 v[76:79], v[66:67], off
	global_load_dwordx4 v[72:75], v[68:69], off
	ds_read_b32 v101, v99
	s_movk_i32 s10, 0x2200
	v_mul_lo_u32 v97, v228, s10
	v_or_b32_e32 v98, 24, v110
	v_or_b32_e32 v96, 28, v110
	s_waitcnt lgkmcnt(0)
	v_rcp_f32_e32 v101, v101
	v_mad_i64_i32 v[66:67], s[4:5], v98, s45, v[64:65]
	v_mad_i64_i32 v[64:65], s[4:5], v96, s45, v[64:65]
	v_add_u32_e32 v97, s33, v97
	v_lshl_add_u32 v103, v227, 1, v97
	s_movk_i32 s4, 0x440
	v_mul_f32_e32 v0, v0, v101
	global_load_dwordx4 v[68:71], v[66:67], off
	s_nop 0
	global_load_dwordx4 v[64:67], v[64:65], off
	v_mad_u32_u24 v105, v226, s4, v103
	v_cvt_pk_bf16_f32 v0, v0, v177
	ds_write_b16 v105, v0
	v_mul_f32_e32 v0, v48, v101
	v_cvt_pk_bf16_f32 v0, v0, v177
	ds_write_b16 v105, v0 offset:64
	v_mul_f32_e32 v0, v32, v101
	v_cvt_pk_bf16_f32 v0, v0, v177
	ds_write_b16 v105, v0 offset:128
	v_mul_f32_e32 v0, v16, v101
	v_cvt_pk_bf16_f32 v0, v0, v177
	ds_read_b32 v16, v99 offset:4
	ds_write_b16 v105, v0 offset:192
	v_lshl_or_b32 v0, v226, 2, 1
	s_movk_i32 s4, 0x110
	v_mad_u32_u24 v0, v0, s4, v103
	s_waitcnt lgkmcnt(1)
	v_rcp_f32_e32 v16, v16
	s_add_u32 s4, s3, s6
	s_addc_u32 s5, s2, s7
	v_ashrrev_i32_e32 v111, 31, v110
	v_mul_f32_e32 v1, v1, v16
	v_cvt_pk_bf16_f32 v1, v1, v177
	ds_write_b16 v0, v1
	v_mul_f32_e32 v1, v49, v16
	v_cvt_pk_bf16_f32 v1, v1, v177
	ds_write_b16 v0, v1 offset:64
	v_mul_f32_e32 v1, v33, v16
	v_cvt_pk_bf16_f32 v1, v1, v177
	ds_write_b16 v0, v1 offset:128
	v_mul_f32_e32 v1, v17, v16
	v_cvt_pk_bf16_f32 v1, v1, v177
	ds_read_b32 v16, v99 offset:8
	ds_write_b16 v0, v1 offset:192
	v_ashrrev_i32_e32 v109, 31, v108
	v_ashrrev_i32_e32 v107, 31, v106
	v_ashrrev_i32_e32 v105, 31, v104
	s_waitcnt lgkmcnt(1)
	v_rcp_f32_e32 v16, v16
	v_ashrrev_i32_e32 v103, 31, v102
	v_ashrrev_i32_e32 v101, 31, v100
	s_add_i32 s9, s9, s13
	v_mul_f32_e32 v1, v2, v16
	v_cvt_pk_bf16_f32 v1, v1, v177
	ds_write_b16 v0, v1 offset:272
	v_mul_f32_e32 v1, v50, v16
	v_cvt_pk_bf16_f32 v1, v1, v177
	ds_write_b16 v0, v1 offset:336
	v_mul_f32_e32 v1, v34, v16
	v_cvt_pk_bf16_f32 v1, v1, v177
	ds_write_b16 v0, v1 offset:400
	v_mul_f32_e32 v1, v18, v16
	v_cvt_pk_bf16_f32 v1, v1, v177
	ds_read_b32 v2, v99 offset:12
	ds_write_b16 v0, v1 offset:464
	s_cmpk_gt_i32 s9, 0x1ff
	s_waitcnt lgkmcnt(1)
	v_rcp_f32_e32 v2, v2
	s_nop 0
	v_mul_f32_e32 v1, v3, v2
	v_cvt_pk_bf16_f32 v1, v1, v177
	ds_write_b16 v0, v1 offset:544
	v_mul_f32_e32 v1, v51, v2
	v_cvt_pk_bf16_f32 v1, v1, v177
	ds_write_b16 v0, v1 offset:608
	v_mul_f32_e32 v1, v35, v2
	v_cvt_pk_bf16_f32 v1, v1, v177
	ds_write_b16 v0, v1 offset:672
	v_mul_f32_e32 v1, v19, v2
	v_cvt_pk_bf16_f32 v1, v1, v177
	ds_write_b16 v0, v1 offset:736
	ds_read_b32 v1, v99 offset:32
	s_waitcnt lgkmcnt(0)
	v_rcp_f32_e32 v1, v1
	s_nop 0
	v_mul_f32_e32 v2, v4, v1
	v_cvt_pk_bf16_f32 v2, v2, v177
	ds_write_b16 v0, v2 offset:1904
	v_mul_f32_e32 v2, v52, v1
	v_cvt_pk_bf16_f32 v2, v2, v177
	ds_write_b16 v0, v2 offset:1968
	v_mul_f32_e32 v2, v36, v1
	v_cvt_pk_bf16_f32 v2, v2, v177
	v_mul_f32_e32 v1, v20, v1
	ds_write_b16 v0, v2 offset:2032
	v_cvt_pk_bf16_f32 v1, v1, v177
	ds_read_b32 v2, v99 offset:36
	ds_write_b16 v0, v1 offset:2096
	s_waitcnt lgkmcnt(1)
	v_rcp_f32_e32 v2, v2
	s_nop 0
	v_mul_f32_e32 v1, v5, v2
	v_cvt_pk_bf16_f32 v1, v1, v177
	ds_write_b16 v0, v1 offset:2176
	v_mul_f32_e32 v1, v53, v2
	v_cvt_pk_bf16_f32 v1, v1, v177
	ds_write_b16 v0, v1 offset:2240
	v_mul_f32_e32 v1, v37, v2
	v_cvt_pk_bf16_f32 v1, v1, v177
	ds_write_b16 v0, v1 offset:2304
	v_mul_f32_e32 v1, v21, v2
	v_cvt_pk_bf16_f32 v1, v1, v177
	ds_read_b32 v2, v99 offset:40
	ds_write_b16 v0, v1 offset:2368
	s_waitcnt lgkmcnt(1)
	v_rcp_f32_e32 v2, v2
	s_nop 0
	v_mul_f32_e32 v1, v6, v2
	v_cvt_pk_bf16_f32 v1, v1, v177
	ds_write_b16 v0, v1 offset:2448
	v_mul_f32_e32 v1, v54, v2
	v_cvt_pk_bf16_f32 v1, v1, v177
	ds_write_b16 v0, v1 offset:2512
	v_mul_f32_e32 v1, v38, v2
	v_cvt_pk_bf16_f32 v1, v1, v177
	ds_write_b16 v0, v1 offset:2576
	v_mul_f32_e32 v1, v22, v2
	v_cvt_pk_bf16_f32 v1, v1, v177
	ds_read_b32 v2, v99 offset:44
	ds_write_b16 v0, v1 offset:2640
	s_waitcnt vmcnt(7)
	v_lshlrev_b32_e32 v6, 16, v92
	s_waitcnt lgkmcnt(1)
	v_rcp_f32_e32 v2, v2
	s_nop 0
	v_mul_f32_e32 v1, v7, v2
	v_cvt_pk_bf16_f32 v1, v1, v177
	ds_write_b16 v0, v1 offset:2720
	v_mul_f32_e32 v1, v55, v2
	v_cvt_pk_bf16_f32 v1, v1, v177
	ds_write_b16 v0, v1 offset:2784
	v_mul_f32_e32 v1, v39, v2
	v_cvt_pk_bf16_f32 v1, v1, v177
	ds_write_b16 v0, v1 offset:2848
	v_mul_f32_e32 v1, v23, v2
	v_cvt_pk_bf16_f32 v1, v1, v177
	ds_write_b16 v0, v1 offset:2912
	ds_read_b32 v1, v99 offset:64
	s_waitcnt lgkmcnt(0)
	v_rcp_f32_e32 v1, v1
	s_nop 0
	v_mul_f32_e32 v2, v8, v1
	v_cvt_pk_bf16_f32 v2, v2, v177
	ds_write_b16 v0, v2 offset:4080
	v_mul_f32_e32 v2, v56, v1
	v_cvt_pk_bf16_f32 v2, v2, v177
	ds_write_b16 v0, v2 offset:4144
	v_mul_f32_e32 v2, v40, v1
	v_cvt_pk_bf16_f32 v2, v2, v177
	v_mul_f32_e32 v1, v24, v1
	ds_write_b16 v0, v2 offset:4208
	v_cvt_pk_bf16_f32 v1, v1, v177
	ds_read_b32 v2, v99 offset:68
	ds_write_b16 v0, v1 offset:4272
	s_waitcnt lgkmcnt(1)
	v_rcp_f32_e32 v2, v2
	s_nop 0
	v_mul_f32_e32 v1, v9, v2
	v_cvt_pk_bf16_f32 v1, v1, v177
	ds_write_b16 v0, v1 offset:4352
	v_mul_f32_e32 v1, v57, v2
	v_cvt_pk_bf16_f32 v1, v1, v177
	ds_write_b16 v0, v1 offset:4416
	v_mul_f32_e32 v1, v41, v2
	v_cvt_pk_bf16_f32 v1, v1, v177
	ds_write_b16 v0, v1 offset:4480
	v_mul_f32_e32 v1, v25, v2
	v_cvt_pk_bf16_f32 v1, v1, v177
	ds_read_b32 v2, v99 offset:72
	ds_write_b16 v0, v1 offset:4544
	s_waitcnt lgkmcnt(1)
	v_rcp_f32_e32 v2, v2
	s_nop 0
	v_mul_f32_e32 v1, v10, v2
	v_cvt_pk_bf16_f32 v1, v1, v177
	ds_write_b16 v0, v1 offset:4624
	v_mul_f32_e32 v1, v58, v2
	v_cvt_pk_bf16_f32 v1, v1, v177
	ds_write_b16 v0, v1 offset:4688
	v_mul_f32_e32 v1, v42, v2
	v_cvt_pk_bf16_f32 v1, v1, v177
	ds_write_b16 v0, v1 offset:4752
	v_mul_f32_e32 v1, v26, v2
	v_cvt_pk_bf16_f32 v1, v1, v177
	ds_read_b32 v2, v99 offset:76
	ds_write_b16 v0, v1 offset:4816
	s_waitcnt lgkmcnt(1)
	v_rcp_f32_e32 v2, v2
	s_nop 0
	v_mul_f32_e32 v1, v11, v2
	v_cvt_pk_bf16_f32 v1, v1, v177
	ds_write_b16 v0, v1 offset:4896
	v_mul_f32_e32 v1, v59, v2
	v_cvt_pk_bf16_f32 v1, v1, v177
	ds_write_b16 v0, v1 offset:4960
	v_mul_f32_e32 v1, v43, v2
	v_cvt_pk_bf16_f32 v1, v1, v177
	ds_write_b16 v0, v1 offset:5024
	v_mul_f32_e32 v1, v27, v2
	v_cvt_pk_bf16_f32 v1, v1, v177
	ds_write_b16 v0, v1 offset:5088
	ds_read_b32 v1, v99 offset:96
	v_lshlrev_b64 v[10:11], 13, v[110:111]
	s_waitcnt lgkmcnt(0)
	v_rcp_f32_e32 v1, v1
	s_nop 0
	v_mul_f32_e32 v2, v12, v1
	v_cvt_pk_bf16_f32 v2, v2, v177
	ds_write_b16 v0, v2 offset:6256
	v_mul_f32_e32 v2, v60, v1
	v_cvt_pk_bf16_f32 v2, v2, v177
	ds_write_b16 v0, v2 offset:6320
	v_mul_f32_e32 v2, v44, v1
	v_cvt_pk_bf16_f32 v2, v2, v177
	v_mul_f32_e32 v1, v28, v1
	ds_write_b16 v0, v2 offset:6384
	v_cvt_pk_bf16_f32 v1, v1, v177
	ds_read_b32 v2, v99 offset:100
	ds_write_b16 v0, v1 offset:6448
	s_waitcnt lgkmcnt(1)
	v_rcp_f32_e32 v2, v2
	s_nop 0
	v_mul_f32_e32 v1, v13, v2
	v_cvt_pk_bf16_f32 v1, v1, v177
	ds_write_b16 v0, v1 offset:6528
	v_mul_f32_e32 v1, v61, v2
	v_cvt_pk_bf16_f32 v1, v1, v177
	ds_write_b16 v0, v1 offset:6592
	v_mul_f32_e32 v1, v45, v2
	v_cvt_pk_bf16_f32 v1, v1, v177
	ds_write_b16 v0, v1 offset:6656
	v_mul_f32_e32 v1, v29, v2
	v_cvt_pk_bf16_f32 v1, v1, v177
	ds_read_b32 v2, v99 offset:104
	ds_write_b16 v0, v1 offset:6720
	s_waitcnt lgkmcnt(1)
	v_rcp_f32_e32 v2, v2
	s_nop 0
	v_mul_f32_e32 v1, v14, v2
	v_cvt_pk_bf16_f32 v1, v1, v177
	ds_write_b16 v0, v1 offset:6800
	v_mul_f32_e32 v1, v62, v2
	v_cvt_pk_bf16_f32 v1, v1, v177
	ds_write_b16 v0, v1 offset:6864
	v_mul_f32_e32 v1, v46, v2
	v_cvt_pk_bf16_f32 v1, v1, v177
	ds_write_b16 v0, v1 offset:6928
	v_mul_f32_e32 v1, v30, v2
	v_cvt_pk_bf16_f32 v1, v1, v177
	ds_read_b32 v2, v99 offset:108
	ds_write_b16 v0, v1 offset:6992
	v_ashrrev_i32_e32 v99, 31, v98
	s_waitcnt lgkmcnt(1)
	v_rcp_f32_e32 v2, v2
	s_nop 0
	v_mul_f32_e32 v1, v15, v2
	v_cvt_pk_bf16_f32 v1, v1, v177
	ds_write_b16 v0, v1 offset:7072
	v_mul_f32_e32 v1, v63, v2
	v_cvt_pk_bf16_f32 v1, v1, v177
	ds_write_b16 v0, v1 offset:7136
	v_mul_f32_e32 v1, v47, v2
	v_cvt_pk_bf16_f32 v1, v1, v177
	ds_write_b16 v0, v1 offset:7200
	v_mul_f32_e32 v1, v31, v2
	v_cvt_pk_bf16_f32 v1, v1, v177
	ds_write_b16 v0, v1 offset:7264
	v_mul_u32_u24_e32 v0, 0x110, v112
	s_waitcnt lgkmcnt(0)
	v_add3_u32 v12, v97, v188, v0
	ds_read_b128 v[2:5], v12
	v_lshl_add_u64 v[0:1], s[4:5], 0, v[176:177]
	v_lshl_add_u64 v[0:1], v[0:1], 0, s[60:61]
	v_lshl_add_u64 v[10:11], v[0:1], 0, v[10:11]
	v_ashrrev_i32_e32 v97, 31, v96
	s_waitcnt lgkmcnt(0)
	v_lshlrev_b32_e32 v7, 16, v2
	v_mul_f32_e32 v6, v7, v6
	v_and_b32_e32 v2, 0xffff0000, v2
	v_and_b32_e32 v7, 0xffff0000, v92
	v_mul_f32_e32 v2, v2, v7
	v_cvt_pk_bf16_f32 v2, v6, v2
	v_lshlrev_b32_e32 v6, 16, v93
	v_lshlrev_b32_e32 v7, 16, v3
	v_mul_f32_e32 v6, v7, v6
	v_and_b32_e32 v3, 0xffff0000, v3
	v_and_b32_e32 v7, 0xffff0000, v93
	v_mul_f32_e32 v3, v3, v7
	v_cvt_pk_bf16_f32 v3, v6, v3
	v_lshlrev_b32_e32 v6, 16, v94
	v_lshlrev_b32_e32 v7, 16, v4
	v_mul_f32_e32 v6, v7, v6
	v_and_b32_e32 v4, 0xffff0000, v4
	v_and_b32_e32 v7, 0xffff0000, v94
	v_mul_f32_e32 v4, v4, v7
	v_cvt_pk_bf16_f32 v4, v6, v4
	v_lshlrev_b32_e32 v6, 16, v95
	v_lshlrev_b32_e32 v7, 16, v5
	v_mul_f32_e32 v6, v7, v6
	v_and_b32_e32 v5, 0xffff0000, v5
	v_and_b32_e32 v7, 0xffff0000, v95
	v_mul_f32_e32 v5, v5, v7
	v_cvt_pk_bf16_f32 v5, v6, v5
	ds_read_b128 v[6:9], v12 offset:1088
	global_store_dwordx4 v[10:11], v[2:5], off
	v_lshlrev_b64 v[10:11], 13, v[108:109]
	v_lshl_add_u64 v[10:11], v[0:1], 0, v[10:11]
	s_waitcnt vmcnt(7)
	v_lshlrev_b32_e32 v2, 16, v88
	s_waitcnt lgkmcnt(0)
	v_lshlrev_b32_e32 v3, 16, v6
	v_mul_f32_e32 v2, v3, v2
	v_and_b32_e32 v3, 0xffff0000, v6
	v_and_b32_e32 v4, 0xffff0000, v88
	v_mul_f32_e32 v3, v3, v4
	v_cvt_pk_bf16_f32 v2, v2, v3
	v_lshlrev_b32_e32 v3, 16, v89
	v_lshlrev_b32_e32 v4, 16, v7
	v_mul_f32_e32 v3, v4, v3
	v_and_b32_e32 v4, 0xffff0000, v7
	v_and_b32_e32 v5, 0xffff0000, v89
	v_mul_f32_e32 v4, v4, v5
	v_cvt_pk_bf16_f32 v3, v3, v4
	v_lshlrev_b32_e32 v4, 16, v90
	v_lshlrev_b32_e32 v5, 16, v8
	v_mul_f32_e32 v4, v5, v4
	v_and_b32_e32 v5, 0xffff0000, v8
	v_and_b32_e32 v6, 0xffff0000, v90
	v_mul_f32_e32 v5, v5, v6
	v_cvt_pk_bf16_f32 v4, v4, v5
	v_lshlrev_b32_e32 v5, 16, v91
	v_lshlrev_b32_e32 v6, 16, v9
	v_mul_f32_e32 v5, v6, v5
	v_and_b32_e32 v6, 0xffff0000, v9
	v_and_b32_e32 v7, 0xffff0000, v91
	v_mul_f32_e32 v6, v6, v7
	v_cvt_pk_bf16_f32 v5, v5, v6
	ds_read_b128 v[6:9], v12 offset:2176
	global_store_dwordx4 v[10:11], v[2:5], off
	v_lshlrev_b64 v[10:11], 13, v[106:107]
	v_lshl_add_u64 v[10:11], v[0:1], 0, v[10:11]
	s_waitcnt vmcnt(7)
	v_lshlrev_b32_e32 v2, 16, v84
	s_waitcnt lgkmcnt(0)
	v_lshlrev_b32_e32 v3, 16, v6
	v_mul_f32_e32 v2, v3, v2
	v_and_b32_e32 v3, 0xffff0000, v6
	v_and_b32_e32 v4, 0xffff0000, v84
	v_mul_f32_e32 v3, v3, v4
	v_cvt_pk_bf16_f32 v2, v2, v3
	v_lshlrev_b32_e32 v3, 16, v85
	v_lshlrev_b32_e32 v4, 16, v7
	v_mul_f32_e32 v3, v4, v3
	v_and_b32_e32 v4, 0xffff0000, v7
	v_and_b32_e32 v5, 0xffff0000, v85
	v_mul_f32_e32 v4, v4, v5
	v_cvt_pk_bf16_f32 v3, v3, v4
	v_lshlrev_b32_e32 v4, 16, v86
	v_lshlrev_b32_e32 v5, 16, v8
	v_mul_f32_e32 v4, v5, v4
	v_and_b32_e32 v5, 0xffff0000, v8
	v_and_b32_e32 v6, 0xffff0000, v86
	v_mul_f32_e32 v5, v5, v6
	v_cvt_pk_bf16_f32 v4, v4, v5
	v_lshlrev_b32_e32 v5, 16, v87
	v_lshlrev_b32_e32 v6, 16, v9
	v_mul_f32_e32 v5, v6, v5
	v_and_b32_e32 v6, 0xffff0000, v9
	v_and_b32_e32 v7, 0xffff0000, v87
	v_mul_f32_e32 v6, v6, v7
	v_cvt_pk_bf16_f32 v5, v5, v6
	ds_read_b128 v[6:9], v12 offset:3264
	global_store_dwordx4 v[10:11], v[2:5], off
	v_lshlrev_b64 v[10:11], 13, v[104:105]
	v_lshl_add_u64 v[10:11], v[0:1], 0, v[10:11]
	s_waitcnt vmcnt(7)
	v_lshlrev_b32_e32 v2, 16, v80
	s_waitcnt lgkmcnt(0)
	v_lshlrev_b32_e32 v3, 16, v6
	v_mul_f32_e32 v2, v3, v2
	v_and_b32_e32 v3, 0xffff0000, v6
	v_and_b32_e32 v4, 0xffff0000, v80
	v_mul_f32_e32 v3, v3, v4
	v_cvt_pk_bf16_f32 v2, v2, v3
	v_lshlrev_b32_e32 v3, 16, v81
	v_lshlrev_b32_e32 v4, 16, v7
	v_mul_f32_e32 v3, v4, v3
	v_and_b32_e32 v4, 0xffff0000, v7
	v_and_b32_e32 v5, 0xffff0000, v81
	v_mul_f32_e32 v4, v4, v5
	v_cvt_pk_bf16_f32 v3, v3, v4
	v_lshlrev_b32_e32 v4, 16, v82
	v_lshlrev_b32_e32 v5, 16, v8
	v_mul_f32_e32 v4, v5, v4
	v_and_b32_e32 v5, 0xffff0000, v8
	v_and_b32_e32 v6, 0xffff0000, v82
	v_mul_f32_e32 v5, v5, v6
	v_cvt_pk_bf16_f32 v4, v4, v5
	v_lshlrev_b32_e32 v5, 16, v83
	v_lshlrev_b32_e32 v6, 16, v9
	v_mul_f32_e32 v5, v6, v5
	v_and_b32_e32 v6, 0xffff0000, v9
	v_and_b32_e32 v7, 0xffff0000, v83
	v_mul_f32_e32 v6, v6, v7
	v_cvt_pk_bf16_f32 v5, v5, v6
	ds_read_b128 v[6:9], v12 offset:4352
	global_store_dwordx4 v[10:11], v[2:5], off
	v_lshlrev_b64 v[10:11], 13, v[102:103]
	v_lshl_add_u64 v[10:11], v[0:1], 0, v[10:11]
	s_waitcnt vmcnt(7)
	v_lshlrev_b32_e32 v2, 16, v76
	s_waitcnt lgkmcnt(0)
	v_lshlrev_b32_e32 v3, 16, v6
	v_mul_f32_e32 v2, v3, v2
	v_and_b32_e32 v3, 0xffff0000, v6
	v_and_b32_e32 v4, 0xffff0000, v76
	v_mul_f32_e32 v3, v3, v4
	v_cvt_pk_bf16_f32 v2, v2, v3
	v_lshlrev_b32_e32 v3, 16, v77
	v_lshlrev_b32_e32 v4, 16, v7
	v_mul_f32_e32 v3, v4, v3
	v_and_b32_e32 v4, 0xffff0000, v7
	v_and_b32_e32 v5, 0xffff0000, v77
	v_mul_f32_e32 v4, v4, v5
	v_cvt_pk_bf16_f32 v3, v3, v4
	v_lshlrev_b32_e32 v4, 16, v78
	v_lshlrev_b32_e32 v5, 16, v8
	v_mul_f32_e32 v4, v5, v4
	v_and_b32_e32 v5, 0xffff0000, v8
	v_and_b32_e32 v6, 0xffff0000, v78
	v_mul_f32_e32 v5, v5, v6
	v_cvt_pk_bf16_f32 v4, v4, v5
	v_lshlrev_b32_e32 v5, 16, v79
	v_lshlrev_b32_e32 v6, 16, v9
	v_mul_f32_e32 v5, v6, v5
	v_and_b32_e32 v6, 0xffff0000, v9
	v_and_b32_e32 v7, 0xffff0000, v79
	v_mul_f32_e32 v6, v6, v7
	v_cvt_pk_bf16_f32 v5, v5, v6
	ds_read_b128 v[6:9], v12 offset:5440
	global_store_dwordx4 v[10:11], v[2:5], off
	v_lshlrev_b64 v[10:11], 13, v[100:101]
	v_lshl_add_u64 v[10:11], v[0:1], 0, v[10:11]
	s_waitcnt vmcnt(7)
	v_lshlrev_b32_e32 v2, 16, v72
	s_waitcnt lgkmcnt(0)
	v_lshlrev_b32_e32 v3, 16, v6
	v_mul_f32_e32 v2, v3, v2
	v_and_b32_e32 v3, 0xffff0000, v6
	v_and_b32_e32 v4, 0xffff0000, v72
	v_mul_f32_e32 v3, v3, v4
	v_cvt_pk_bf16_f32 v2, v2, v3
	v_lshlrev_b32_e32 v3, 16, v73
	v_lshlrev_b32_e32 v4, 16, v7
	v_mul_f32_e32 v3, v4, v3
	v_and_b32_e32 v4, 0xffff0000, v7
	v_and_b32_e32 v5, 0xffff0000, v73
	v_mul_f32_e32 v4, v4, v5
	v_cvt_pk_bf16_f32 v3, v3, v4
	v_lshlrev_b32_e32 v4, 16, v74
	v_lshlrev_b32_e32 v5, 16, v8
	v_mul_f32_e32 v4, v5, v4
	v_and_b32_e32 v5, 0xffff0000, v8
	v_and_b32_e32 v6, 0xffff0000, v74
	v_mul_f32_e32 v5, v5, v6
	v_cvt_pk_bf16_f32 v4, v4, v5
	v_lshlrev_b32_e32 v5, 16, v75
	v_lshlrev_b32_e32 v6, 16, v9
	v_mul_f32_e32 v5, v6, v5
	v_and_b32_e32 v6, 0xffff0000, v9
	v_and_b32_e32 v7, 0xffff0000, v75
	v_mul_f32_e32 v6, v6, v7
	v_cvt_pk_bf16_f32 v5, v5, v6
	ds_read_b128 v[6:9], v12 offset:6528
	global_store_dwordx4 v[10:11], v[2:5], off
	v_lshlrev_b64 v[10:11], 13, v[98:99]
	v_lshl_add_u64 v[10:11], v[0:1], 0, v[10:11]
	s_waitcnt vmcnt(7)
	v_lshlrev_b32_e32 v2, 16, v68
	s_waitcnt lgkmcnt(0)
	v_lshlrev_b32_e32 v3, 16, v6
	v_mul_f32_e32 v2, v3, v2
	v_and_b32_e32 v3, 0xffff0000, v6
	v_and_b32_e32 v4, 0xffff0000, v68
	v_mul_f32_e32 v3, v3, v4
	v_cvt_pk_bf16_f32 v2, v2, v3
	v_lshlrev_b32_e32 v3, 16, v69
	v_lshlrev_b32_e32 v4, 16, v7
	v_mul_f32_e32 v3, v4, v3
	v_and_b32_e32 v4, 0xffff0000, v7
	v_and_b32_e32 v5, 0xffff0000, v69
	v_mul_f32_e32 v4, v4, v5
	v_cvt_pk_bf16_f32 v3, v3, v4
	v_lshlrev_b32_e32 v4, 16, v70
	v_lshlrev_b32_e32 v5, 16, v8
	v_mul_f32_e32 v4, v5, v4
	v_and_b32_e32 v5, 0xffff0000, v8
	v_and_b32_e32 v6, 0xffff0000, v70
	v_mul_f32_e32 v5, v5, v6
	v_cvt_pk_bf16_f32 v4, v4, v5
	v_lshlrev_b32_e32 v5, 16, v71
	v_lshlrev_b32_e32 v6, 16, v9
	v_mul_f32_e32 v5, v6, v5
	v_and_b32_e32 v6, 0xffff0000, v9
	v_and_b32_e32 v7, 0xffff0000, v71
	v_mul_f32_e32 v6, v6, v7
	v_cvt_pk_bf16_f32 v5, v5, v6
	ds_read_b128 v[6:9], v12 offset:7616
	global_store_dwordx4 v[10:11], v[2:5], off
	s_waitcnt vmcnt(7)
	s_nop 0
	v_lshlrev_b32_e32 v2, 16, v64
	s_waitcnt lgkmcnt(0)
	v_lshlrev_b32_e32 v3, 16, v6
	v_mul_f32_e32 v2, v3, v2
	v_and_b32_e32 v3, 0xffff0000, v6
	v_and_b32_e32 v4, 0xffff0000, v64
	v_mul_f32_e32 v3, v3, v4
	v_cvt_pk_bf16_f32 v2, v2, v3
	v_lshlrev_b32_e32 v3, 16, v65
	v_lshlrev_b32_e32 v4, 16, v7
	v_mul_f32_e32 v3, v4, v3
	v_and_b32_e32 v4, 0xffff0000, v7
	v_and_b32_e32 v5, 0xffff0000, v65
	v_mul_f32_e32 v4, v4, v5
	v_cvt_pk_bf16_f32 v3, v3, v4
	v_lshlrev_b32_e32 v4, 16, v66
	v_lshlrev_b32_e32 v5, 16, v8
	v_mul_f32_e32 v4, v5, v4
	v_and_b32_e32 v5, 0xffff0000, v8
	v_and_b32_e32 v6, 0xffff0000, v66
	v_mul_f32_e32 v5, v5, v6
	v_cvt_pk_bf16_f32 v4, v4, v5
	v_lshlrev_b32_e32 v5, 16, v67
	v_lshlrev_b32_e32 v6, 16, v9
	v_mul_f32_e32 v5, v6, v5
	v_and_b32_e32 v6, 0xffff0000, v9
	v_and_b32_e32 v7, 0xffff0000, v67
	v_mul_f32_e32 v6, v6, v7
	v_cvt_pk_bf16_f32 v5, v5, v6
	v_lshlrev_b64 v[6:7], 13, v[96:97]
	v_lshl_add_u64 v[0:1], v[0:1], 0, v[6:7]
	global_store_dwordx4 v[0:1], v[2:5], off
	s_cbranch_scc1 .LBB0_727
.LBB0_708:
	s_cmp_ge_u32 s92, 3
	s_cbranch_scc1 .Ltq2_exit
	s_add_u32 s2, s12, 0x100
	s_cmp_lg_u32 s9, s2
	s_cbranch_scc1 .Ltq2_exit
	s_cmpk_lg_i32 s13, 0x100
	s_cbranch_scc1 .Ltq2_exit
	s_bfe_u32 s2, s12, 0x20003
	s_cmp_lg_u32 s2, 1
	s_cbranch_scc1 .Ltq2_exit

.Ltq2_exit:
	s_waitcnt vmcnt(0)
	v_mov_b32_e32 v177, 0
	s_mov_b64 s[2:3], s[0:1]
	s_mov_b32 s4, s12
	s_mov_b32 s5, s13
	s_load_dwordx2 s[4:5], s[2:3], 0x70
	s_load_dwordx2 s[34:35], s[2:3], 0xe8
	s_lshl_b64 s[2:3], s[50:51], 2
	v_mov_b32_e32 v145, v220
	s_waitcnt lgkmcnt(0)
	s_add_u32 s4, s4, s2
	s_addc_u32 s5, s5, s3
	s_add_u32 s2, s34, 0x200000
	s_addc_u32 s3, s35, 0
	s_bfe_u32 s6, s9, 0x10002
	s_lshl_b32 s10, s6, 12
	s_or_b32 s11, s10, 0x2000
	s_lshl_b32 s10, s9, 5
	s_lshl_b32 s6, s6, 20
	s_and_b32 s7, s9, 3
	s_and_b32 s22, s10, 0xf00
	s_add_i32 s6, s6, s8
	s_and_b32 s16, s9, 0xffffff80
	s_or_b32 s10, s11, s22
	s_lshl_b32 s6, s6, 1
	s_lshl_b32 s15, s7, 8
	s_add_u32 s6, s34, s6
	s_addc_u32 s18, s35, 0
	s_add_u32 s20, s6, s15
	s_addc_u32 s21, s18, 0
	s_add_u32 s48, s20, 0x600000
	s_addc_u32 s49, s21, 0
	s_add_u32 s56, s20, 0xa00000
	s_addc_u32 s57, s21, 0
	s_lshl_b32 s6, s11, 10
	s_add_u32 s6, s34, s6
	s_addc_u32 s11, s35, 0
	s_add_u32 s6, s6, s15
	s_addc_u32 s11, s11, 0
	s_add_u32 s36, s6, 0x68600000
	s_addc_u32 s43, s11, 0
	s_add_u32 s44, s6, 0x69600000
	s_addc_u32 s52, s11, 0
	s_mul_i32 s6, s10, 0x4800
	s_add_u32 s6, s34, s6
	s_addc_u32 s15, s35, 0
	s_add_u32 s11, s6, 0x2e600000
	s_addc_u32 s15, s15, 0
	s_lshl_b32 s6, s7, 9
	s_add_i32 s6, s6, s16
	v_ashrrev_i32_e32 v136, 4, v145
	s_ashr_i32 s7, s6, 31
	v_add_u32_e32 v138, 32, v136
	s_lshl_b64 s[6:7], s[6:7], 1
	v_lshlrev_b32_e32 v18, 3, v145
	v_ashrrev_i32_e32 v137, 31, v136
	v_ashrrev_i32_e32 v139, 31, v138
	s_add_u32 s18, s11, s6
	v_ashrrev_i32_e32 v228, 6, v145
	v_and_b32_e32 v144, 0x78, v18
	v_lshlrev_b64 v[132:133], 10, v[136:137]
	v_lshlrev_b64 v[134:135], 10, v[138:139]
	s_addc_u32 s19, s15, s7
	v_and_b32_e32 v227, 31, v145
	v_lshlrev_b32_e32 v188, 1, v144
	v_lshl_add_u64 v[0:1], s[56:57], 0, v[132:133]
	v_mov_b32_e32 v189, v177
	v_lshl_add_u64 v[2:3], s[56:57], 0, v[134:135]
	v_lshlrev_b32_e32 v229, 5, v228
	v_bfe_u32 v226, v145, 5, 1
	v_lshl_add_u64 v[0:1], v[0:1], 0, v[188:189]
	v_lshl_add_u64 v[2:3], v[2:3], 0, v[188:189]
	v_or_b32_e32 v19, v229, v227
	v_mov_b64_e32 v[16:17], s[18:19]
	global_load_dwordx4 v[8:11], v[0:1], off
	global_load_dwordx4 v[4:7], v[2:3], off
	v_lshl_add_u64 v[0:1], s[48:49], 0, v[132:133]
	v_lshl_add_u64 v[2:3], s[48:49], 0, v[134:135]
	v_mad_i64_i32 v[16:17], s[18:19], v19, s45, v[16:17]
	v_lshlrev_b32_e32 v190, 4, v226
	v_mov_b32_e32 v191, v177
	v_lshl_add_u64 v[0:1], v[0:1], 0, v[188:189]
	v_lshl_add_u64 v[2:3], v[2:3], 0, v[188:189]
	v_lshl_add_u64 v[16:17], v[16:17], 0, v[190:191]
	global_load_dwordx4 v[12:15], v[0:1], off
	s_nop 0
	global_load_dwordx4 v[0:3], v[2:3], off
	s_barrier
	global_load_dwordx4 v[162:165], v[16:17], off offset:160
	global_load_dwordx4 v[166:169], v[16:17], off offset:224
	v_and_b32_e32 v20, 32, v145
	global_load_dwordx4 v[154:157], v20, s[4:5] offset:464
	global_load_dwordx4 v[32:35], v20, s[4:5] offset:336
	global_load_dwordx4 v[178:181], v[16:17], off offset:128
	global_load_dwordx4 v[182:185], v[16:17], off offset:192
	global_load_dwordx4 v[44:47], v20, s[4:5] offset:320
	global_load_dwordx4 v[192:195], v20, s[4:5] offset:448
	global_load_dwordx4 v[120:123], v[16:17], off
	global_load_dwordx4 v[128:131], v[16:17], off offset:32
	global_load_dwordx4 v[200:203], v20, s[4:5] offset:400
	global_load_dwordx4 v[80:83], v20, s[4:5] offset:272
	global_load_dwordx4 v[210:213], v20, s[4:5] offset:384
	global_load_dwordx4 v[88:91], v20, s[4:5] offset:256
	global_load_dwordx4 v[116:119], v[16:17], off offset:64
	global_load_dwordx4 v[232:235], v[16:17], off offset:96
	global_load_dwordx4 v[108:111], v20, s[4:5]
	global_load_dwordx4 v[104:107], v20, s[4:5] offset:16
	global_load_dwordx4 v[100:103], v20, s[4:5] offset:64
	global_load_dwordx4 v[96:99], v20, s[4:5] offset:80
	global_load_dwordx4 v[112:115], v20, s[4:5] offset:128
	global_load_dwordx4 v[124:127], v20, s[4:5] offset:144
	global_load_dwordx4 v[236:239], v20, s[4:5] offset:192
	global_load_dwordx4 v[240:243], v20, s[4:5] offset:208
	v_and_b32_e32 v21, 0xfffff0, v136
	v_lshlrev_b32_e32 v22, 1, v136
	v_and_or_b32 v21, v22, 8, v21
	v_lshrrev_b32_e32 v22, 1, v136
	v_and_b32_e32 v23, 3, v136
	v_and_or_b32 v22, v22, 4, v23
	v_and_b32_e32 v23, 0xfffff0, v138
	v_lshlrev_b32_e32 v24, 1, v138
	v_and_or_b32 v23, v24, 8, v23
	v_lshrrev_b32_e32 v21, 1, v21
	v_bfe_u32 v18, v18, 5, 2
	v_lshrrev_b32_e32 v23, 1, v23
	v_or_b32_e32 v21, v21, v18
	v_or_b32_e32 v18, v23, v18
	v_lshlrev_b32_e32 v21, 9, v21
	v_lshlrev_b32_e32 v22, 6, v22
	v_lshlrev_b32_e32 v18, 9, v18
	v_and_b32_e32 v16, 48, v188
	v_or3_b32 v191, v18, v22, v16
	v_or3_b32 v231, v21, v22, v16
	v_or_b32_e32 v16, s22, v227
	v_add_u32_e32 v16, v16, v229
	v_ashrrev_i32_e32 v16, 1, v16
	v_and_b32_e32 v16, 0xffffffe0, v16
	v_ashrrev_i32_e32 v17, 31, v16
	v_lshl_add_u64 v[16:17], v[16:17], 3, s[2:3]
	v_lshlrev_b32_e32 v176, 6, v226
	v_lshl_add_u64 v[16:17], v[16:17], 0, v[176:177]
	global_load_dwordx4 v[68:71], v[16:17], off offset:48
	global_load_dwordx4 v[76:79], v[16:17], off offset:32
	global_load_dwordx4 v[84:87], v[16:17], off offset:16
	global_load_dwordx4 v[92:95], v[16:17], off
	global_load_dwordx4 v[48:51], v[16:17], off offset:176
	global_load_dwordx4 v[56:59], v[16:17], off offset:160
	global_load_dwordx4 v[64:67], v[16:17], off offset:144
	global_load_dwordx4 v[72:75], v[16:17], off offset:128
	v_lshlrev_b32_e32 v16, 8, v19
	v_and_b32_e32 v16, 0x3f00, v16
	v_mov_b32_e32 v17, v177
	v_lshl_add_u64 v[16:17], s[2:3], 0, v[16:17]
	v_lshl_add_u64 v[36:37], v[16:17], 0, v[176:177]
	global_load_dwordx4 v[28:31], v[36:37], off offset:48
	global_load_dwordx4 v[40:43], v[36:37], off offset:32
	global_load_dwordx4 v[52:55], v[36:37], off offset:16
	global_load_dwordx4 v[60:63], v[36:37], off
	global_load_dwordx4 v[16:19], v[36:37], off offset:176
	global_load_dwordx4 v[20:23], v[36:37], off offset:160
	global_load_dwordx4 v[24:27], v[36:37], off offset:144
	s_nop 0
	global_load_dwordx4 v[36:39], v[36:37], off offset:128
	v_lshlrev_b32_e32 v230, 4, v145
	s_add_i32 s2, 0, 0x10000
	s_cmp_lg_u32 0, -1
	s_cselect_b32 s4, 0, 0
	s_mov_b32 s16, s17
	s_mov_b32 s18, s17
	s_mov_b32 s19, s17
	s_mov_b32 s24, s17
	s_mov_b32 s25, s17
	s_mov_b32 s26, s17
	s_mov_b32 s27, s17
	s_mov_b32 s28, s17
	s_mov_b32 s29, s17
	s_mov_b32 s30, s17
	s_mov_b32 s31, s17
	s_mov_b32 s85, 4
	v_lshlrev_b32_e32 v176, 1, v144
	s_waitcnt vmcnt(31)
	v_lshlrev_b32_e32 v225, 16, v123
	v_mov_b32_e32 v146, v156
	v_mov_b32_e32 v152, v154
	v_lshlrev_b32_e32 v141, 16, v165
	v_lshlrev_b32_e32 v140, 16, v169
	v_and_b32_e32 v142, 0xffff0000, v169
	v_lshlrev_b32_e32 v154, 16, v167
	v_and_b32_e32 v156, 0xffff0000, v167
	v_lshlrev_b32_e32 v167, 16, v181
	v_and_b32_e32 v169, 0xffff0000, v181
	s_waitcnt vmcnt(21)
	v_mov_b32_e32 v181, v102
	s_waitcnt vmcnt(17)
	v_mov_b32_e32 v102, v239
	v_lshlrev_b32_e32 v239, 16, v120
	v_and_b32_e32 v143, 0xffff0000, v165
	v_mov_b32_e32 v165, v44
	v_mov_b32_e32 v44, v193
	v_lshlrev_b32_e32 v175, 16, v180
	v_and_b32_e32 v193, 0xffff0000, v180
	s_waitcnt vmcnt(16)
	v_mov_b32_e32 v218, v240
	v_mov_b32_e32 v219, v96
	v_mov_b32_e32 v96, v241
	v_mov_b32_e32 v180, v238
	v_and_b32_e32 v241, 0xffff0000, v120
	v_lshlrev_b32_e32 v238, 16, v116
	v_and_b32_e32 v240, 0xffff0000, v116
	v_mul_f32_e32 v116, v239, v239
	v_mov_b32_e32 v170, v202
	v_mov_b32_e32 v202, v212
	v_mov_b32_e32 v208, v210
	v_lshlrev_b32_e32 v210, 16, v235
	v_and_b32_e32 v212, 0xffff0000, v235
	v_mov_b32_e32 v235, v104
	v_mov_b32_e32 v104, v125
	v_lshlrev_b32_e32 v125, 16, v121
	v_fmac_f32_e32 v116, v241, v241
	v_and_b32_e32 v121, 0xffff0000, v121
	v_fmac_f32_e32 v116, v125, v125
	v_lshlrev_b32_e32 v205, 16, v178
	v_lshlrev_b32_e32 v204, 16, v182
	v_and_b32_e32 v207, 0xffff0000, v178
	v_and_b32_e32 v206, 0xffff0000, v182
	v_lshlrev_b32_e32 v178, 16, v233
	v_and_b32_e32 v182, 0xffff0000, v233
	v_mov_b32_e32 v233, v106
	v_mov_b32_e32 v106, v127
	v_lshlrev_b32_e32 v127, 16, v122
	v_fmac_f32_e32 v116, v121, v121
	v_mov_b32_e32 v187, v100
	v_mov_b32_e32 v100, v237
	v_and_b32_e32 v237, 0xffff0000, v122
	v_fmac_f32_e32 v116, v127, v127
	v_fmac_f32_e32 v116, v237, v237
	v_and_b32_e32 v123, 0xffff0000, v123
	v_fmac_f32_e32 v116, v225, v225
	v_mov_b32_e32 v147, v34
	v_mov_b32_e32 v34, v157
	v_lshlrev_b32_e32 v148, 16, v168
	v_mov_b32_e32 v153, v32
	v_and_b32_e32 v150, 0xffff0000, v168
	v_mov_b32_e32 v32, v155
	v_lshlrev_b32_e32 v155, 16, v163
	v_and_b32_e32 v157, 0xffff0000, v163
	v_lshlrev_b32_e32 v161, 16, v162
	v_lshlrev_b32_e32 v160, 16, v166
	v_and_b32_e32 v163, 0xffff0000, v162
	v_and_b32_e32 v162, 0xffff0000, v166
	v_lshlrev_b32_e32 v166, 16, v185
	v_and_b32_e32 v168, 0xffff0000, v185
	v_lshlrev_b32_e32 v185, 16, v128
	v_fmac_f32_e32 v116, v123, v123
	v_mov_b32_e32 v158, v194
	v_mov_b32_e32 v159, v46
	v_mov_b32_e32 v46, v195
	v_mov_b32_e32 v194, v200
	v_mov_b32_e32 v195, v80
	v_mov_b32_e32 v80, v201
	v_lshlrev_b32_e32 v197, 16, v179
	v_lshlrev_b32_e32 v196, 16, v183
	v_and_b32_e32 v201, 0xffff0000, v179
	v_and_b32_e32 v200, 0xffff0000, v183
	v_lshlrev_b32_e32 v179, 16, v129
	v_and_b32_e32 v183, 0xffff0000, v129
	v_and_b32_e32 v129, 0xffff0000, v128
	v_fmac_f32_e32 v116, v185, v185
	v_fmac_f32_e32 v116, v129, v129
	v_fmac_f32_e32 v116, v179, v179
	v_lshlrev_b32_e32 v217, 16, v130
	v_fmac_f32_e32 v116, v183, v183
	v_mov_b32_e32 v171, v82
	v_mov_b32_e32 v82, v203
	v_mov_b32_e32 v203, v90
	v_mov_b32_e32 v90, v213
	v_mov_b32_e32 v209, v88
	v_mov_b32_e32 v88, v211
	v_lshlrev_b32_e32 v211, 16, v131
	v_and_b32_e32 v213, 0xffff0000, v131
	v_and_b32_e32 v131, 0xffff0000, v130
	v_fmac_f32_e32 v116, v217, v217
	v_fmac_f32_e32 v116, v131, v131
	v_fmac_f32_e32 v116, v211, v211
	v_fmac_f32_e32 v116, v213, v213
	v_lshlrev_b32_e32 v216, 16, v234
	v_and_b32_e32 v130, 0xffff0000, v234
	v_mov_b32_e32 v234, v124
	v_lshlrev_b32_e32 v124, 16, v117
	v_and_b32_e32 v120, 0xffff0000, v117
	v_pk_fma_f32 v[116:117], v[238:239], v[238:239], v[116:117] op_sel_hi:[1,1,0]
	v_lshlrev_b32_e32 v149, 16, v164
	v_pk_fma_f32 v[116:117], v[240:241], v[240:241], v[116:117]
	v_and_b32_e32 v151, 0xffff0000, v164
	v_pk_fma_f32 v[116:117], v[124:125], v[124:125], v[116:117]
	v_mov_b32_e32 v164, v192
	v_lshlrev_b32_e32 v174, 16, v184
	v_and_b32_e32 v192, 0xffff0000, v184
	v_lshlrev_b32_e32 v184, 16, v232
	v_and_b32_e32 v128, 0xffff0000, v232
	v_mov_b32_e32 v232, v126
	v_lshlrev_b32_e32 v126, 16, v118
	v_pk_fma_f32 v[116:117], v[120:121], v[120:121], v[116:117]
	v_mov_b32_e32 v186, v236
	v_and_b32_e32 v236, 0xffff0000, v118
	v_pk_fma_f32 v[116:117], v[126:127], v[126:127], v[116:117]
	v_lshlrev_b32_e32 v224, 16, v119
	v_pk_fma_f32 v[116:117], v[236:237], v[236:237], v[116:117]
	v_and_b32_e32 v122, 0xffff0000, v119
	v_pk_fma_f32 v[116:117], v[224:225], v[224:225], v[116:117]
	v_mul_f32_e32 v118, v205, v205
	v_pk_fma_f32 v[116:117], v[122:123], v[122:123], v[116:117]
	v_mov_b32_e32 v214, v242
	v_pk_fma_f32 v[116:117], v[184:185], v[184:185], v[116:117]
	v_mov_b32_e32 v215, v98
	v_pk_fma_f32 v[116:117], v[128:129], v[128:129], v[116:117]
	v_mov_b32_e32 v98, v243
	v_pk_fma_f32 v[116:117], v[178:179], v[178:179], v[116:117]
	v_mov_b32_e32 v242, v156
	v_pk_fma_f32 v[116:117], v[182:183], v[182:183], v[116:117]
	v_mov_b32_e32 v243, v154
	v_pk_fma_f32 v[116:117], v[216:217], v[216:217], v[116:117]
	v_mov_b32_e32 v198, v150
	v_pk_fma_f32 v[116:117], v[130:131], v[130:131], v[116:117]
	v_mov_b32_e32 v199, v148
	v_pk_fma_f32 v[116:117], v[210:211], v[210:211], v[116:117]
	v_mov_b32_e32 v172, v142
	v_pk_fma_f32 v[116:117], v[212:213], v[212:213], v[116:117]
	v_mov_b32_e32 v173, v140
	v_pk_add_f32 v[116:117], v[118:119], v[116:117] op_sel_hi:[0,1]
	v_mul_f32_e32 v118, v207, v207
	v_pk_add_f32 v[116:117], v[118:119], v[116:117] op_sel_hi:[0,1]
	v_mul_f32_e32 v118, v197, v197
	v_pk_add_f32 v[116:117], v[118:119], v[116:117] op_sel_hi:[0,1]
	v_mul_f32_e32 v118, v201, v201
	v_pk_add_f32 v[116:117], v[118:119], v[116:117] op_sel_hi:[0,1]
	v_mul_f32_e32 v118, v175, v175
	v_pk_add_f32 v[116:117], v[118:119], v[116:117] op_sel_hi:[0,1]
	v_mul_f32_e32 v118, v193, v193
	v_pk_add_f32 v[116:117], v[118:119], v[116:117] op_sel_hi:[0,1]
	v_mul_f32_e32 v118, v167, v167
	v_pk_add_f32 v[116:117], v[118:119], v[116:117] op_sel_hi:[0,1]
	v_mul_f32_e32 v118, v169, v169
	v_pk_add_f32 v[116:117], v[118:119], v[116:117] op_sel_hi:[0,1]
	v_mul_f32_e32 v118, v161, v161
	v_pk_add_f32 v[116:117], v[118:119], v[116:117] op_sel_hi:[0,1]
	v_mul_f32_e32 v118, v163, v163
	v_pk_add_f32 v[116:117], v[118:119], v[116:117] op_sel_hi:[0,1]
	v_mul_f32_e32 v118, v155, v155
	v_pk_add_f32 v[116:117], v[118:119], v[116:117] op_sel_hi:[0,1]
	v_mul_f32_e32 v118, v157, v157
	v_pk_add_f32 v[116:117], v[118:119], v[116:117] op_sel_hi:[0,1]
	v_mul_f32_e32 v118, v149, v149
	v_pk_add_f32 v[116:117], v[118:119], v[116:117] op_sel_hi:[0,1]
	v_mul_f32_e32 v118, v151, v151
	v_pk_add_f32 v[116:117], v[118:119], v[116:117] op_sel_hi:[0,1]
	v_mul_f32_e32 v118, v141, v141
	v_pk_add_f32 v[116:117], v[118:119], v[116:117] op_sel_hi:[0,1]
	v_mul_f32_e32 v118, v143, v143
	v_pk_add_f32 v[116:117], v[118:119], v[116:117] op_sel_hi:[0,1]
	v_pk_fma_f32 v[116:117], v[204:205], v[204:205], v[116:117]
	v_mul_f32_e32 v118, v154, v154
	v_pk_fma_f32 v[116:117], v[206:207], v[206:207], v[116:117]
	s_nop 0
	v_pk_fma_f32 v[116:117], v[196:197], v[196:197], v[116:117]
	s_nop 0
	v_pk_fma_f32 v[116:117], v[200:201], v[200:201], v[116:117]
	s_nop 0
	v_pk_fma_f32 v[116:117], v[174:175], v[174:175], v[116:117]
	s_nop 0
	v_pk_fma_f32 v[116:117], v[192:193], v[192:193], v[116:117]
	s_nop 0
	v_pk_fma_f32 v[116:117], v[166:167], v[166:167], v[116:117]
	s_nop 0
	v_pk_fma_f32 v[116:117], v[168:169], v[168:169], v[116:117]
	s_nop 0
	v_pk_fma_f32 v[116:117], v[160:161], v[160:161], v[116:117]
	s_nop 0
	v_pk_fma_f32 v[116:117], v[162:163], v[162:163], v[116:117]
	s_nop 0
	v_pk_add_f32 v[116:117], v[118:119], v[116:117] op_sel_hi:[0,1]
	v_mov_b32_e32 v119, v110
	v_pk_fma_f32 v[116:117], v[242:243], v[242:243], v[116:117]
	v_mul_f32_e32 v110, v148, v148
	v_pk_add_f32 v[116:117], v[110:111], v[116:117] op_sel_hi:[0,1]
	v_pk_fma_f32 v[116:117], v[198:199], v[198:199], v[116:117]
	v_mul_f32_e32 v110, v140, v140
	v_pk_add_f32 v[116:117], v[110:111], v[116:117] op_sel_hi:[0,1]
	v_pk_fma_f32 v[116:117], v[172:173], v[172:173], v[116:117]
	v_mov_b32_e32 v118, v114
	v_mov_b32_e32 v110, v116
	s_nop 1
	v_permlane32_swap_b32_e32 v116, v110
	v_add_f32_e32 v110, v116, v110
	v_fmamk_f32 v110, v110, 0x3c000000, v221
	v_mul_f32_e32 v114, 0x4b800000, v110
	v_cmp_gt_f32_e32 vcc, s42, v110
	s_nop 1
	v_cndmask_b32_e32 v110, v110, v114, vcc
	v_rsq_f32_e32 v116, v110
	v_mov_b32_e32 v110, v115
	v_mov_b32_e32 v115, v108
	v_mov_b32_e32 v114, v112
	v_mul_f32_e32 v108, 0x45800000, v116
	v_cndmask_b32_e32 v112, v116, v108, vcc
	v_pk_mul_f32 v[114:115], v[114:115], v[112:113] op_sel_hi:[1,0]
	v_mov_b32_e32 v108, v113
	v_pk_mul_f32 v[114:115], v[114:115], v[238:239]
	v_pk_mul_f32 v[116:117], v[234:235], v[112:113] op_sel_hi:[1,0]
	v_pk_mul_f32 v[108:109], v[108:109], v[112:113] op_sel_hi:[1,0]
	v_pk_mul_f32 v[118:119], v[118:119], v[112:113] op_sel_hi:[1,0]
	v_pk_mul_f32 v[110:111], v[110:111], v[112:113] op_sel_hi:[1,0]
	v_pk_mul_f32 v[106:107], v[106:107], v[112:113] op_sel_hi:[1,0]
	v_pk_mul_f32 v[100:101], v[100:101], v[112:113] op_sel_hi:[1,0]
	v_pk_mul_f32 v[96:97], v[96:97], v[112:113] op_sel_hi:[1,0]
	v_pk_mul_f32 v[172:173], v[112:113], v[194:195] op_sel_hi:[0,1]
	v_pk_mul_f32 v[32:33], v[112:113], v[32:33] op_sel_hi:[0,1]
	v_pk_mul_f32 v[116:117], v[116:117], v[126:127]
	v_pk_mul_f32 v[108:109], v[108:109], v[240:241]
	v_pk_mul_f32 v[104:105], v[104:105], v[112:113] op_sel_hi:[1,0]
	v_pk_mul_f32 v[118:119], v[118:119], v[124:125]
	v_pk_mul_f32 v[124:125], v[232:233], v[112:113] op_sel_hi:[1,0]
	v_pk_mul_f32 v[110:111], v[110:111], v[120:121]
	v_pk_mul_f32 v[106:107], v[106:107], v[122:123]
	v_pk_mul_f32 v[120:121], v[186:187], v[112:113] op_sel_hi:[1,0]
	v_pk_mul_f32 v[122:123], v[218:219], v[112:113] op_sel_hi:[1,0]
	v_pk_mul_f32 v[100:101], v[100:101], v[128:129]
	v_pk_mul_f32 v[96:97], v[96:97], v[130:131]
	v_pk_mul_f32 v[126:127], v[180:181], v[112:113] op_sel_hi:[1,0]
	v_pk_mul_f32 v[128:129], v[214:215], v[112:113] op_sel_hi:[1,0]
	v_pk_mul_f32 v[102:103], v[102:103], v[112:113] op_sel_hi:[1,0]
	v_pk_mul_f32 v[98:99], v[98:99], v[112:113] op_sel_hi:[1,0]
	v_pk_mul_f32 v[130:131], v[112:113], v[208:209] op_sel_hi:[0,1]
	v_pk_mul_f32 v[172:173], v[172:173], v[174:175]
	v_pk_mul_f32 v[88:89], v[112:113], v[88:89] op_sel_hi:[0,1]
	v_pk_mul_f32 v[80:81], v[112:113], v[80:81] op_sel_hi:[0,1]
	v_pk_mul_f32 v[174:175], v[112:113], v[202:203] op_sel_hi:[0,1]
	v_pk_mul_f32 v[170:171], v[112:113], v[170:171] op_sel_hi:[0,1]
	v_pk_mul_f32 v[90:91], v[112:113], v[90:91] op_sel_hi:[0,1]
	v_pk_mul_f32 v[82:83], v[112:113], v[82:83] op_sel_hi:[0,1]
	v_pk_mul_f32 v[164:165], v[112:113], v[164:165] op_sel_hi:[0,1]
	v_pk_mul_f32 v[152:153], v[112:113], v[152:153] op_sel_hi:[0,1]
	v_pk_mul_f32 v[44:45], v[112:113], v[44:45] op_sel_hi:[0,1]
	v_pk_mul_f32 v[32:33], v[32:33], v[150:151]
	v_pk_mul_f32 v[150:151], v[112:113], v[158:159] op_sel_hi:[0,1]
	v_pk_mul_f32 v[146:147], v[112:113], v[146:147] op_sel_hi:[0,1]
	v_pk_mul_f32 v[46:47], v[112:113], v[46:47] op_sel_hi:[0,1]
	v_pk_mul_f32 v[34:35], v[112:113], v[34:35] op_sel_hi:[0,1]
	s_waitcnt vmcnt(12)
	v_pk_mul_f32 v[112:113], v[114:115], v[92:93] op_sel:[1,0] op_sel_hi:[0,1]
	v_pk_mul_f32 v[92:93], v[114:115], v[92:93]
	v_sub_f32_e32 v112, v112, v113
	v_add_f32_e32 v113, v93, v92
	v_pk_mul_f32 v[92:93], v[108:109], v[94:95] op_sel:[1,0] op_sel_hi:[0,1]
	v_sub_f32_e32 v114, v92, v93
	v_pk_mul_f32 v[92:93], v[108:109], v[94:95]
	v_pk_mul_f32 v[104:105], v[104:105], v[236:237]
	v_add_f32_e32 v94, v93, v92
	v_pk_mul_f32 v[92:93], v[118:119], v[84:85] op_sel:[1,0] op_sel_hi:[0,1]
	v_pk_mul_f32 v[84:85], v[118:119], v[84:85]
	v_sub_f32_e32 v92, v92, v93
	v_add_f32_e32 v93, v85, v84
	v_pk_mul_f32 v[84:85], v[110:111], v[86:87] op_sel:[1,0] op_sel_hi:[0,1]
	v_sub_f32_e32 v95, v84, v85
	v_pk_mul_f32 v[84:85], v[110:111], v[86:87]
	v_pk_mul_f32 v[124:125], v[124:125], v[224:225]
	v_add_f32_e32 v86, v85, v84
	v_pk_mul_f32 v[84:85], v[116:117], v[76:77] op_sel:[1,0] op_sel_hi:[0,1]
	v_pk_mul_f32 v[76:77], v[116:117], v[76:77]
	v_sub_f32_e32 v84, v84, v85
	v_add_f32_e32 v85, v77, v76
	v_pk_mul_f32 v[76:77], v[104:105], v[78:79] op_sel:[1,0] op_sel_hi:[0,1]
	v_sub_f32_e32 v87, v76, v77
	v_pk_mul_f32 v[76:77], v[104:105], v[78:79]
	v_pk_mul_f32 v[120:121], v[120:121], v[184:185]
	v_add_f32_e32 v78, v77, v76
	v_pk_mul_f32 v[76:77], v[124:125], v[68:69] op_sel:[1,0] op_sel_hi:[0,1]
	v_pk_mul_f32 v[68:69], v[124:125], v[68:69]
	v_sub_f32_e32 v76, v76, v77
	v_add_f32_e32 v77, v69, v68
	v_pk_mul_f32 v[68:69], v[106:107], v[70:71] op_sel:[1,0] op_sel_hi:[0,1]
	v_sub_f32_e32 v79, v68, v69
	v_pk_mul_f32 v[68:69], v[106:107], v[70:71]
	v_pk_mul_f32 v[126:127], v[126:127], v[178:179]
	v_add_f32_e32 v70, v69, v68
	s_waitcnt vmcnt(8)
	v_pk_mul_f32 v[68:69], v[120:121], v[72:73] op_sel:[1,0] op_sel_hi:[0,1]
	v_sub_f32_e32 v71, v68, v69
	v_pk_mul_f32 v[68:69], v[120:121], v[72:73]
	v_pk_mul_f32 v[102:103], v[102:103], v[182:183]
	v_add_f32_e32 v72, v69, v68
	v_pk_mul_f32 v[68:69], v[100:101], v[74:75] op_sel:[1,0] op_sel_hi:[0,1]
	v_sub_f32_e32 v73, v68, v69
	v_pk_mul_f32 v[68:69], v[100:101], v[74:75]
	v_pk_mul_f32 v[122:123], v[122:123], v[216:217]
	v_add_f32_e32 v74, v69, v68
	v_pk_mul_f32 v[68:69], v[126:127], v[64:65] op_sel:[1,0] op_sel_hi:[0,1]
	v_pk_mul_f32 v[64:65], v[126:127], v[64:65]
	v_sub_f32_e32 v68, v68, v69
	v_add_f32_e32 v69, v65, v64
	v_pk_mul_f32 v[64:65], v[102:103], v[66:67] op_sel:[1,0] op_sel_hi:[0,1]
	v_sub_f32_e32 v75, v64, v65
	v_pk_mul_f32 v[64:65], v[102:103], v[66:67]
	v_pk_mul_f32 v[128:129], v[128:129], v[210:211]
	v_add_f32_e32 v66, v65, v64
	v_pk_mul_f32 v[64:65], v[122:123], v[56:57] op_sel:[1,0] op_sel_hi:[0,1]
	v_pk_mul_f32 v[56:57], v[122:123], v[56:57]
	v_sub_f32_e32 v64, v64, v65
	v_add_f32_e32 v65, v57, v56
	v_pk_mul_f32 v[56:57], v[96:97], v[58:59] op_sel:[1,0] op_sel_hi:[0,1]
	v_sub_f32_e32 v67, v56, v57
	v_pk_mul_f32 v[56:57], v[96:97], v[58:59]
	v_pk_mul_f32 v[98:99], v[98:99], v[212:213]
	v_add_f32_e32 v58, v57, v56
	v_pk_mul_f32 v[56:57], v[128:129], v[48:49] op_sel:[1,0] op_sel_hi:[0,1]
	v_pk_mul_f32 v[48:49], v[128:129], v[48:49]
	v_sub_f32_e32 v56, v56, v57
	v_add_f32_e32 v57, v49, v48
	v_pk_mul_f32 v[48:49], v[98:99], v[50:51] op_sel:[1,0] op_sel_hi:[0,1]
	v_pk_mul_f32 v[130:131], v[130:131], v[204:205]
	v_sub_f32_e32 v59, v48, v49
	v_pk_mul_f32 v[48:49], v[98:99], v[50:51]
	v_pk_mul_f32 v[88:89], v[88:89], v[206:207]
	v_add_f32_e32 v50, v49, v48
	s_waitcnt vmcnt(4)
	v_pk_mul_f32 v[48:49], v[130:131], v[60:61] op_sel:[1,0] op_sel_hi:[0,1]
	v_sub_f32_e32 v51, v48, v49
	v_pk_mul_f32 v[48:49], v[130:131], v[60:61]
	v_pk_mul_f32 v[174:175], v[174:175], v[196:197]
	v_add_f32_e32 v60, v49, v48
	v_pk_mul_f32 v[48:49], v[88:89], v[62:63] op_sel:[1,0] op_sel_hi:[0,1]
	v_sub_f32_e32 v61, v48, v49
	v_pk_mul_f32 v[48:49], v[88:89], v[62:63]
	v_pk_mul_f32 v[90:91], v[90:91], v[200:201]
	v_add_f32_e32 v62, v49, v48
	v_pk_mul_f32 v[48:49], v[174:175], v[52:53] op_sel:[1,0] op_sel_hi:[0,1]
	v_sub_f32_e32 v63, v48, v49
	v_pk_mul_f32 v[48:49], v[174:175], v[52:53]
	v_pk_mul_f32 v[80:81], v[80:81], v[192:193]
	v_add_f32_e32 v52, v49, v48
	v_pk_mul_f32 v[48:49], v[90:91], v[54:55] op_sel:[1,0] op_sel_hi:[0,1]
	v_sub_f32_e32 v53, v48, v49
	v_pk_mul_f32 v[48:49], v[90:91], v[54:55]
	v_pk_mul_f32 v[166:167], v[170:171], v[166:167]
	v_add_f32_e32 v54, v49, v48
	v_pk_mul_f32 v[48:49], v[172:173], v[40:41] op_sel:[1,0] op_sel_hi:[0,1]
	v_pk_mul_f32 v[40:41], v[172:173], v[40:41]
	v_sub_f32_e32 v48, v48, v49
	v_add_f32_e32 v49, v41, v40
	v_pk_mul_f32 v[40:41], v[80:81], v[42:43] op_sel:[1,0] op_sel_hi:[0,1]
	v_sub_f32_e32 v55, v40, v41
	v_pk_mul_f32 v[40:41], v[80:81], v[42:43]
	v_pk_mul_f32 v[82:83], v[82:83], v[168:169]
	v_add_f32_e32 v42, v41, v40
	v_pk_mul_f32 v[40:41], v[166:167], v[28:29] op_sel:[1,0] op_sel_hi:[0,1]
	v_pk_mul_f32 v[28:29], v[166:167], v[28:29]
	v_sub_f32_e32 v40, v40, v41
	v_add_f32_e32 v41, v29, v28
	v_pk_mul_f32 v[28:29], v[82:83], v[30:31] op_sel:[1,0] op_sel_hi:[0,1]
	v_pk_mul_f32 v[160:161], v[164:165], v[160:161]
	v_sub_f32_e32 v43, v28, v29
	v_pk_mul_f32 v[28:29], v[82:83], v[30:31]
	v_pk_mul_f32 v[44:45], v[44:45], v[162:163]
	v_add_f32_e32 v30, v29, v28
	s_waitcnt vmcnt(0)
	v_pk_mul_f32 v[28:29], v[160:161], v[36:37] op_sel:[1,0] op_sel_hi:[0,1]
	v_sub_f32_e32 v31, v28, v29
	v_pk_mul_f32 v[28:29], v[160:161], v[36:37]
	v_pk_mul_f32 v[150:151], v[150:151], v[154:155]
	v_add_f32_e32 v36, v29, v28
	v_pk_mul_f32 v[28:29], v[44:45], v[38:39] op_sel:[1,0] op_sel_hi:[0,1]
	v_sub_f32_e32 v37, v28, v29
	v_pk_mul_f32 v[28:29], v[44:45], v[38:39]
	v_pk_mul_f32 v[46:47], v[46:47], v[156:157]
	v_add_f32_e32 v38, v29, v28
	v_pk_mul_f32 v[28:29], v[150:151], v[24:25] op_sel:[1,0] op_sel_hi:[0,1]
	v_pk_mul_f32 v[24:25], v[150:151], v[24:25]
	v_sub_f32_e32 v28, v28, v29
	v_add_f32_e32 v29, v25, v24
	v_pk_mul_f32 v[24:25], v[46:47], v[26:27] op_sel:[1,0] op_sel_hi:[0,1]
	v_pk_mul_f32 v[148:149], v[152:153], v[148:149]
	v_sub_f32_e32 v39, v24, v25
	v_pk_mul_f32 v[24:25], v[46:47], v[26:27]
	v_pk_mul_f32 v[140:141], v[146:147], v[140:141]
	v_add_f32_e32 v26, v25, v24
	v_pk_mul_f32 v[24:25], v[148:149], v[20:21] op_sel:[1,0] op_sel_hi:[0,1]
	v_pk_mul_f32 v[20:21], v[148:149], v[20:21]
	v_sub_f32_e32 v24, v24, v25
	v_add_f32_e32 v25, v21, v20
	v_pk_mul_f32 v[20:21], v[32:33], v[22:23] op_sel:[1,0] op_sel_hi:[0,1]
	v_sub_f32_e32 v27, v20, v21
	v_pk_mul_f32 v[20:21], v[32:33], v[22:23]
	v_pk_mul_f32 v[34:35], v[34:35], v[142:143]
	v_add_f32_e32 v22, v21, v20
	v_pk_mul_f32 v[20:21], v[140:141], v[16:17] op_sel:[1,0] op_sel_hi:[0,1]
	v_pk_mul_f32 v[16:17], v[140:141], v[16:17]
	v_sub_f32_e32 v20, v20, v21
	v_add_f32_e32 v21, v17, v16
	v_pk_mul_f32 v[16:17], v[34:35], v[18:19] op_sel:[1,0] op_sel_hi:[0,1]
	v_sub_f32_e32 v23, v16, v17
	v_pk_mul_f32 v[16:17], v[34:35], v[18:19]
	v_add_u32_e32 v200, 0, v231
	v_add_u32_e32 v201, 0, v191
	v_add_f32_e32 v16, v17, v16
	v_cvt_pk_bf16_f32 v124, v112, v114
	v_cvt_pk_bf16_f32 v125, v92, v95
	v_cvt_pk_bf16_f32 v126, v84, v87
	v_cvt_pk_bf16_f32 v127, v76, v79
	v_cvt_pk_bf16_f32 v120, v71, v73
	v_cvt_pk_bf16_f32 v121, v68, v75
	v_cvt_pk_bf16_f32 v122, v64, v67
	v_cvt_pk_bf16_f32 v123, v56, v59
	v_cvt_pk_bf16_f32 v116, v113, v94
	v_cvt_pk_bf16_f32 v117, v93, v86
	v_cvt_pk_bf16_f32 v118, v85, v78
	v_cvt_pk_bf16_f32 v119, v77, v70
	v_cvt_pk_bf16_f32 v112, v72, v74
	v_cvt_pk_bf16_f32 v113, v69, v66
	v_cvt_pk_bf16_f32 v114, v65, v58
	v_cvt_pk_bf16_f32 v115, v57, v50
	v_cvt_pk_bf16_f32 v108, v51, v61
	v_cvt_pk_bf16_f32 v109, v63, v53
	v_cvt_pk_bf16_f32 v110, v48, v55
	v_cvt_pk_bf16_f32 v111, v40, v43
	v_cvt_pk_bf16_f32 v104, v31, v37
	v_cvt_pk_bf16_f32 v105, v28, v39
	v_cvt_pk_bf16_f32 v106, v24, v27
	v_cvt_pk_bf16_f32 v107, v20, v23
	v_cvt_pk_bf16_f32 v100, v60, v62
	v_cvt_pk_bf16_f32 v101, v52, v54
	v_cvt_pk_bf16_f32 v102, v49, v42
	v_cvt_pk_bf16_f32 v103, v41, v30
	v_cvt_pk_bf16_f32 v96, v36, v38
	v_cvt_pk_bf16_f32 v97, v29, v26
	v_cvt_pk_bf16_f32 v98, v25, v22
	v_cvt_pk_bf16_f32 v99, v21, v16
	s_waitcnt vmcnt(0)
	ds_write_b128 v200, v[8:11]
	ds_write_b128 v201, v[4:7]
	v_lshlrev_b32_e32 v4, 8, v136
	v_and_b32_e32 v5, 0x70, v145
	v_bitop3_b32 v4, v188, v4, v5 bitop3:0xde
	v_add_u32_e32 v202, 0, v4
	v_lshlrev_b32_e32 v4, 8, v138
	v_bitop3_b32 v4, v188, v4, v5 bitop3:0xde
	v_add_u32_e32 v203, 0, v4
	v_lshlrev_b32_e32 v8, 8, v227
	v_and_b32_e32 v9, 0x70, v230
	ds_write_b128 v202, v[12:15] offset:32768
	ds_write_b128 v203, v[0:3] offset:32768
	v_bitop3_b32 v0, v190, v8, v9 bitop3:0xde
	v_add_u32_e32 v204, 0, v0
	s_waitcnt lgkmcnt(0)
	s_barrier
	ds_read_b128 v[0:3], v204 offset:32768
	ds_read_b128 v[4:7], v204 offset:40960
	s_waitcnt lgkmcnt(1)
	v_mfma_f32_32x32x16_bf16 v[32:47], v[0:3], v[124:127], 0
	v_or_b32_e32 v0, 32, v190
	v_bitop3_b32 v0, v0, v8, v9 bitop3:0xde
	v_add_u32_e32 v207, 0, v0
	v_and_b32_e32 v196, 63, v145
	v_lshlrev_b32_e32 v10, 3, v196
	v_and_b32_e32 v11, 0xc0, v230
	v_lshlrev_b64 v[64:65], 9, v[136:137]
	s_waitcnt lgkmcnt(0)
	v_mfma_f32_32x32x16_bf16 v[16:31], v[4:7], v[124:127], 0
	ds_read_b128 v[0:3], v207 offset:32768
	ds_read_b128 v[4:7], v207 offset:40960
	v_lshlrev_b64 v[66:67], 9, v[138:139]
	v_mov_b32_e32 v197, 0
	v_lshlrev_b64 v[192:193], 1, v[64:65]
	v_lshlrev_b64 v[194:195], 1, v[66:67]
	s_waitcnt lgkmcnt(1)
	v_mfma_f32_32x32x16_bf16 v[32:47], v[0:3], v[120:123], v[32:47]
	v_or_b32_e32 v0, 64, v190
	v_bitop3_b32 v0, v0, v8, v9 bitop3:0xde
	v_add_u32_e32 v209, 0, v0
	s_waitcnt lgkmcnt(0)
	v_mfma_f32_32x32x16_bf16 v[16:31], v[4:7], v[120:123], v[16:31]
	ds_read_b128 v[0:3], v209 offset:32768
	ds_read_b128 v[4:7], v209 offset:40960
	s_waitcnt lgkmcnt(1)
	v_mfma_f32_32x32x16_bf16 v[32:47], v[0:3], v[116:119], v[32:47]
	v_or_b32_e32 v0, 0x60, v190
	v_bitop3_b32 v0, v0, v8, v9 bitop3:0xde
	v_add_u32_e32 v205, 0, v0
	s_waitcnt lgkmcnt(0)
	v_mfma_f32_32x32x16_bf16 v[16:31], v[4:7], v[116:119], v[16:31]
	ds_read_b128 v[0:3], v205 offset:32768
	ds_read_b128 v[4:7], v205 offset:40960
	s_waitcnt lgkmcnt(1)
	v_mfma_f32_32x32x16_bf16 v[32:47], v[0:3], v[112:115], v[32:47]
	v_or_b32_e32 v0, 0x80, v190
	v_bitop3_b32 v0, v0, v8, v9 bitop3:0xde
	v_add_u32_e32 v206, 0, v0
	s_waitcnt lgkmcnt(0)
	v_mfma_f32_32x32x16_bf16 v[16:31], v[4:7], v[112:115], v[16:31]
	ds_read_b128 v[0:3], v206 offset:32768
	ds_read_b128 v[4:7], v206 offset:40960
	s_waitcnt lgkmcnt(1)
	v_mfma_f32_32x32x16_bf16 v[32:47], v[0:3], v[108:111], v[32:47]
	v_or_b32_e32 v0, 0xa0, v190
	v_bitop3_b32 v0, v0, v8, v9 bitop3:0xde
	v_add_u32_e32 v208, 0, v0
	s_waitcnt lgkmcnt(0)
	v_mfma_f32_32x32x16_bf16 v[16:31], v[4:7], v[108:111], v[16:31]
	ds_read_b128 v[0:3], v208 offset:32768
	ds_read_b128 v[4:7], v208 offset:40960
	s_waitcnt lgkmcnt(1)
	v_mfma_f32_32x32x16_bf16 v[32:47], v[0:3], v[104:107], v[32:47]
	v_or_b32_e32 v0, 0xc0, v190
	v_bitop3_b32 v0, v0, v8, v9 bitop3:0xde
	v_add_u32_e32 v210, 0, v0
	ds_read_b128 v[0:3], v210 offset:32768
	s_waitcnt lgkmcnt(1)
	v_mfma_f32_32x32x16_bf16 v[16:31], v[4:7], v[104:107], v[16:31]
	v_and_b32_e32 v4, 0x3fffffc0, v145
	v_lshl_add_u32 v191, v4, 2, s2
	ds_read_b128 v[4:7], v210 offset:40960
	s_waitcnt lgkmcnt(1)
	v_mfma_f32_32x32x16_bf16 v[32:47], v[0:3], v[100:103], v[32:47]
	v_or_b32_e32 v0, 0xe0, v190
	v_bitop3_b32 v0, v0, v8, v9 bitop3:0xde
	v_add_u32_e32 v211, 0, v0
	ds_read_b128 v[0:3], v211 offset:32768
	s_waitcnt lgkmcnt(1)
	v_mfma_f32_32x32x16_bf16 v[16:31], v[4:7], v[100:103], v[16:31]
	v_lshlrev_b32_e32 v5, 1, v145
	v_and_or_b32 v4, v10, 24, v11
	v_and_b32_e32 v5, 32, v5
	v_and_b32_e32 v6, 0x100, v10
	v_or3_b32 v69, v4, v5, v6
	ds_read_b128 v[4:7], v211 offset:40960
	v_add_u32_e32 v199, s4, v69
	s_waitcnt lgkmcnt(1)
	v_mfma_f32_32x32x16_bf16 v[32:47], v[0:3], v[96:99], v[32:47]
	s_waitcnt lgkmcnt(0)
	v_mfma_f32_32x32x16_bf16 v[16:31], v[4:7], v[96:99], v[16:31]
	s_nop 9
	v_max_f32_e32 v0, v33, v33
	v_max_f32_e32 v1, v32, v32
	v_max_f32_e32 v0, v1, v0
	v_max3_f32 v0, v0, v34, v35
	v_max3_f32 v0, v0, v36, v37
	v_max3_f32 v0, v0, v38, v39
	v_max3_f32 v0, v0, v40, v41
	v_max3_f32 v0, v0, v42, v43
	v_max3_f32 v0, v0, v44, v45
	v_max3_f32 v0, v0, v46, v47
	v_max3_f32 v0, v0, v16, v17
	v_max3_f32 v0, v0, v18, v19
	v_max3_f32 v0, v0, v20, v21
	v_max3_f32 v0, v0, v22, v23
	v_max3_f32 v0, v0, v24, v25
	v_max3_f32 v0, v0, v26, v27
	v_max3_f32 v0, v0, v28, v29
	v_max3_f32 v0, v0, v30, v31
	v_mov_b32_e32 v1, v0
	s_nop 1
	v_permlane32_swap_b32_e32 v0, v1
	v_max_f32_e32 v1, v1, v1
	v_max_f32_e32 v0, v0, v0
	v_max_f32_e32 v0, v0, v1
	v_add_f32_e32 v1, 0x7149f2ca, v0
	v_cmp_ge_f32_e32 vcc, s14, v1
	s_cmp_eq_u64 vcc, exec
	s_cselect_b64 vcc, -1, 0
	s_add_u32 s2, s20, 0x610000
	s_addc_u32 s3, s21, 0
	s_add_u32 s22, s20, 0xa10000
	s_addc_u32 s23, s21, 0
	v_max_f32_e32 v68, 0xf149f2ca, v0
	v_lshl_add_u64 v[0:1], s[22:23], 0, v[132:133]
	v_lshl_add_u64 v[2:3], s[22:23], 0, v[134:135]
	v_lshl_add_u64 v[0:1], v[0:1], 0, v[188:189]
	v_lshl_add_u64 v[2:3], v[2:3], 0, v[188:189]
	global_load_dwordx4 v[48:51], v[0:1], off
	global_load_dwordx4 v[52:55], v[2:3], off
	v_lshl_add_u64 v[0:1], s[2:3], 0, v[132:133]
	v_lshl_add_u64 v[2:3], s[2:3], 0, v[134:135]
	s_add_u32 s2, s20, 0x620000
	v_lshl_add_u64 v[0:1], v[0:1], 0, v[188:189]
	s_addc_u32 s3, s21, 0
	v_lshl_add_u64 v[2:3], v[2:3], 0, v[188:189]
	global_load_dwordx4 v[56:59], v[0:1], off
	global_load_dwordx4 v[60:63], v[2:3], off
	s_add_u32 s20, s20, 0xa20000
	v_lshl_add_u64 v[0:1], s[2:3], 0, v[134:135]
	s_addc_u32 s21, s21, 0
	v_lshl_add_u64 v[0:1], v[0:1], 0, v[188:189]
	v_lshl_add_u64 v[2:3], s[2:3], 0, v[132:133]
	v_lshl_add_u64 v[2:3], v[2:3], 0, v[188:189]
	global_load_dwordx4 v[140:143], v[0:1], off
	global_load_dwordx4 v[136:139], v[2:3], off
	v_lshl_add_u64 v[0:1], s[20:21], 0, v[134:135]
	v_lshl_add_u64 v[0:1], v[0:1], 0, v[188:189]
	v_lshl_add_u64 v[2:3], s[20:21], 0, v[132:133]
	v_lshl_add_u64 v[2:3], v[2:3], 0, v[188:189]
	global_load_dwordx4 v[132:135], v[0:1], off
	global_load_dwordx4 v[128:131], v[2:3], off
	v_sub_f32_e32 v0, 0xf149f2ca, v68
	v_mul_f32_e32 v0, 0x3e0293ee, v0
	v_exp_f32_e32 v70, v0
	v_cndmask_b32_e32 v168, v68, v246, vcc
	v_mul_f32_e32 v68, 0xbe0293ee, v168
	v_fmamk_f32 v32, v32, 0x3e0293ee, v68
	v_cndmask_b32_e64 v212, v70, 1.0, vcc
	v_mov_b32_e32 v70, v68
	v_fmamk_f32 v33, v33, 0x3e0293ee, v68
	v_fmamk_f32 v34, v34, 0x3e0293ee, v68
	v_fmamk_f32 v35, v35, 0x3e0293ee, v68
	v_fmamk_f32 v36, v36, 0x3e0293ee, v68
	v_fmamk_f32 v37, v37, 0x3e0293ee, v68
	v_fmamk_f32 v38, v38, 0x3e0293ee, v68
	v_fmamk_f32 v39, v39, 0x3e0293ee, v68
	v_fmamk_f32 v40, v40, 0x3e0293ee, v68
	v_fmamk_f32 v41, v41, 0x3e0293ee, v68
	v_fmamk_f32 v42, v42, 0x3e0293ee, v68
	v_fmamk_f32 v43, v43, 0x3e0293ee, v68
	v_fmamk_f32 v44, v44, 0x3e0293ee, v68
	v_fmamk_f32 v45, v45, 0x3e0293ee, v68
	v_fmamk_f32 v46, v46, 0x3e0293ee, v68
	v_fmac_f32_e32 v70, 0x3e0293ee, v47
	s_mov_b32 s20, s17
	s_mov_b32 s21, s17
	s_mov_b32 s22, s17
	s_mov_b32 s23, s17
	v_mov_b64_e32 v[0:1], s[16:17]
	v_exp_f32_e32 v216, v32
	v_exp_f32_e32 v230, v33
	v_exp_f32_e32 v174, v34
	v_exp_f32_e32 v219, v35
	v_exp_f32_e32 v173, v36
	v_exp_f32_e32 v175, v37
	v_exp_f32_e32 v163, v38
	v_exp_f32_e32 v172, v39
	v_exp_f32_e32 v164, v40
	v_exp_f32_e32 v171, v41
	v_exp_f32_e32 v165, v42
	v_exp_f32_e32 v170, v43
	v_exp_f32_e32 v166, v44
	v_exp_f32_e32 v169, v45
	v_exp_f32_e32 v145, v46
	v_exp_f32_e32 v167, v70
	v_mov_b64_e32 v[14:15], s[30:31]
	s_waitcnt vmcnt(4)
	v_mov_b64_e32 v[2:3], s[18:19]
	v_mov_b64_e32 v[4:5], s[20:21]
	v_mov_b64_e32 v[6:7], s[22:23]
	v_mov_b64_e32 v[8:9], s[24:25]
	v_mov_b64_e32 v[10:11], s[26:27]
	v_mov_b64_e32 v[12:13], s[28:29]
	v_pk_fma_f32 v[152:153], v[30:31], s[88:89], v[68:69] op_sel_hi:[1,0,0]
	v_pk_fma_f32 v[154:155], v[28:29], s[88:89], v[68:69] op_sel_hi:[1,0,0]
	v_pk_fma_f32 v[160:161], v[26:27], s[88:89], v[68:69] op_sel_hi:[1,0,0]
	v_pk_fma_f32 v[146:147], v[24:25], s[88:89], v[68:69] op_sel_hi:[1,0,0]
	v_pk_fma_f32 v[148:149], v[22:23], s[88:89], v[68:69] op_sel_hi:[1,0,0]
	v_pk_fma_f32 v[150:151], v[20:21], s[88:89], v[68:69] op_sel_hi:[1,0,0]
	v_pk_fma_f32 v[156:157], v[18:19], s[88:89], v[68:69] op_sel_hi:[1,0,0]
	v_pk_fma_f32 v[158:159], v[16:17], s[88:89], v[68:69] op_sel_hi:[1,0,0]
	s_waitcnt vmcnt(7)
	ds_write_b128 v200, v[48:51] offset:16384
	s_waitcnt vmcnt(6)
	ds_write_b128 v201, v[52:55] offset:16384
	s_waitcnt vmcnt(5)
	ds_write_b128 v202, v[56:59] offset:49152
	s_waitcnt vmcnt(4)
	ds_write_b128 v203, v[60:63] offset:49152
	s_addk_i32 s4, 0x4000
	v_mov_b64_e32 v[62:63], v[14:15]
	v_mov_b64_e32 v[46:47], v[14:15]
	v_mov_b64_e32 v[30:31], v[14:15]
	v_cmp_gt_u32_e64 s[2:3], 32, v196
	v_lshl_add_u32 v189, v227, 2, v191
	v_add_u32_e32 v198, s4, v69
	v_mov_b64_e32 v[60:61], v[12:13]
	v_mov_b64_e32 v[58:59], v[10:11]
	v_mov_b64_e32 v[56:57], v[8:9]
	v_mov_b64_e32 v[54:55], v[6:7]
	v_mov_b64_e32 v[52:53], v[4:5]
	v_mov_b64_e32 v[50:51], v[2:3]
	v_mov_b64_e32 v[48:49], v[0:1]
	v_mov_b64_e32 v[44:45], v[12:13]
	v_mov_b64_e32 v[42:43], v[10:11]
	v_mov_b64_e32 v[40:41], v[8:9]
	v_mov_b64_e32 v[38:39], v[6:7]
	v_mov_b64_e32 v[36:37], v[4:5]
	v_mov_b64_e32 v[34:35], v[2:3]
	v_mov_b64_e32 v[32:33], v[0:1]
	v_mov_b64_e32 v[28:29], v[12:13]
	v_mov_b64_e32 v[26:27], v[10:11]
	v_mov_b64_e32 v[24:25], v[8:9]
	v_mov_b64_e32 v[22:23], v[6:7]
	v_mov_b64_e32 v[20:21], v[4:5]
	v_mov_b64_e32 v[18:19], v[2:3]
	v_mov_b64_e32 v[16:17], v[0:1]
	s_waitcnt lgkmcnt(0)
	s_barrier
	v_add_u32_e32 v222, v192, v176
	v_add_u32_e32 v243, v194, v176

.LBB0_727:
	s_cmp_ge_u32 s92, 3
	s_cbranch_scc1 .Ltq3_exit
	s_cmpk_lg_i32 s13, 0x100
	s_cbranch_scc1 .Ltq3_exit
	s_bfe_u32 s2, s12, 0x20003
	s_cmp_lg_u32 s2, 2
	s_cbranch_scc1 .Ltq3_exit

.Ltq3_exit:
	s_waitcnt vmcnt(0)
	v_mov_b32_e32 v177, 0
	v_readlane_b32 s2, v255, 36
	v_readlane_b32 s3, v255, 37
	s_andn2_b64 vcc, exec, s[2:3]
	v_readlane_b32 s16, v255, 49
	v_readlane_b32 s24, v255, 48
	v_mov_b64_e32 v[224:225], 0x3ff
	s_cbranch_vccz .LBB0_738

.LBB0_774:
	s_cmp_ge_u32 s92, 3
	s_cbranch_scc1 .Ltq4_exit
	s_cmpk_lg_i32 s13, 0x100
	s_cbranch_scc1 .Ltq4_exit
	s_bfe_u32 s2, s12, 0x20003
	s_cmp_lg_u32 s2, 3
	s_cbranch_scc1 .Ltq4_exit
